# static s_setprio 1 for waves 4-7 for the whole kernel (younger half priority raise)
# baseline (speedup 1.0000x reference)
; DI void prologue(const Params& p, unsigned char* smem) {
;   const int WT_TASKS_L = 456 + 256 + 64 + 64 + 128 + 704 + 352;
;   const int N_WT = 2 * WT_TASKS_L;
;   const int N_ADA = 384, N_CK = 512, N_CV = 1024;
;   const int total = N_WT + N_ADA + N_CK + N_CV;
;   for (int task = blockIdx.x; task < total; task += gridDim.x) {
;     if (task < N_WT) {
;       const int l = task / WT_TASKS_L; int t = task % WT_TASKS_L;
;       if (t < 456) { transpose_task(p.in[12] + (size_t)l * 1024 * 3592, 3592, (u16*)(p.ws + WS_WT_IN) + (size_t)l * 3584 * 1024, 1024, 1, t / 57, t % 57, smem); continue; }
; __global__ void __launch_bounds__(NTHR) fwd_megakernel(Params p) {
;   extern __shared__ __attribute__((aligned(16))) unsigned char smem[];
;   cg::grid_group grid = cg::this_grid();
;     ...
;   unsigned* bar = (unsigned*)(p.ws + WS_CTR);
;   unsigned epoch = 0;
;   if (PH & 1) prologue(p, smem);
_Z14fwd_megakernel6Params:
	s_load_dwordx16 s[4:19], s[0:1], 0x0
	s_load_dwordx16 s[68:83], s[0:1], 0xc0
	s_load_dword s87, s[0:1], 0x100
	s_add_u32 s48, s0, 0x100
	s_addc_u32 s49, s1, 0
	s_waitcnt lgkmcnt(0)
	v_writelane_b32 v252, s4, 0
	s_cmpk_lt_i32 s2, 0x1750
	v_and_b32_e32 v212, 0x3ff, v0
	v_writelane_b32 v252, s5, 1
	v_writelane_b32 v252, s6, 2
	v_writelane_b32 v252, s7, 3
	v_writelane_b32 v252, s8, 4
	v_writelane_b32 v252, s9, 5
	v_writelane_b32 v252, s10, 6
	v_writelane_b32 v252, s11, 7
	v_writelane_b32 v252, s12, 8
	v_writelane_b32 v252, s13, 9
	v_writelane_b32 v252, s14, 10
	v_writelane_b32 v252, s15, 11
	v_writelane_b32 v252, s16, 12
	v_writelane_b32 v252, s17, 13
	v_writelane_b32 v252, s18, 14
	v_writelane_b32 v252, s19, 15
	s_load_dwordx16 s[4:19], s[0:1], 0x40
	s_waitcnt lgkmcnt(0)
	v_writelane_b32 v252, s4, 16
	s_nop 1
	v_writelane_b32 v252, s5, 17
	v_writelane_b32 v252, s6, 18
	v_writelane_b32 v252, s7, 19
	v_writelane_b32 v252, s8, 20
	v_writelane_b32 v252, s9, 21
	v_writelane_b32 v252, s10, 22
	v_writelane_b32 v252, s11, 23
	v_writelane_b32 v252, s12, 24
	v_writelane_b32 v252, s13, 25
	v_writelane_b32 v252, s14, 26
	v_writelane_b32 v252, s15, 27
	v_writelane_b32 v252, s16, 28
	v_writelane_b32 v252, s17, 29
	v_writelane_b32 v252, s18, 30
	v_writelane_b32 v252, s19, 31
	s_load_dwordx16 s[4:19], s[0:1], 0x80
	s_waitcnt lgkmcnt(0)
	v_writelane_b32 v252, s4, 32
	s_nop 1
	v_writelane_b32 v252, s5, 33
	v_writelane_b32 v252, s6, 34
	v_writelane_b32 v252, s7, 35
	v_writelane_b32 v252, s8, 36
	v_writelane_b32 v252, s9, 37
	v_writelane_b32 v252, s10, 38
	v_writelane_b32 v252, s11, 39
	v_writelane_b32 v252, s12, 40
	v_writelane_b32 v252, s13, 41
	v_writelane_b32 v252, s14, 42
	v_writelane_b32 v252, s15, 43
	v_writelane_b32 v252, s16, 44
	v_writelane_b32 v252, s17, 45
	v_writelane_b32 v252, s18, 46
	v_writelane_b32 v252, s19, 47
	s_cselect_b64 s[4:5], -1, 0
	v_readfirstlane_b32 s33, v212
	s_nop 3
	s_lshr_b32 s33, s33, 6
	s_cmp_ge_u32 s33, 4
	s_cbranch_scc0 .Lprio_done
	s_setprio 1
.Lprio_done:
	v_writelane_b32 v252, s2, 48
	s_cmpk_gt_i32 s2, 0x174f
	s_cbranch_scc1 .LBB0_74
	s_add_u32 s18, s82, 0x53f3800
	s_addc_u32 s19, s83, 0
	s_add_u32 s0, s82, 0x4363800
	s_addc_u32 s1, s83, 0
	s_add_u32 s6, s82, 0x3f00000
	s_addc_u32 s7, s83, 0
	s_add_u32 s20, s82, 0x3400000
	s_addc_u32 s21, s83, 0
	s_add_u32 s22, s82, 0x1e00000
	s_addc_u32 s23, s83, 0
	s_add_u32 s24, s82, 0x1a00000
	s_addc_u32 s25, s83, 0
	s_add_u32 s26, s82, 0x1800000
	s_addc_u32 s27, s83, 0
	s_add_u32 s28, s82, 0x1600000
	s_addc_u32 s29, s83, 0
	s_add_u32 s30, s82, 0xe00000
	s_addc_u32 s31, s83, 0
	s_mov_b32 s9, 0
	v_mov_b32_e32 v19, 0
	s_movk_i32 s33, 0x104
	s_mov_b32 s34, 0x20000
	s_mov_b32 s35, 0x108000
	s_movk_i32 s36, 0x400
	s_movk_i32 s37, 0x6000
	s_add_i32 s38, 0, 0x14040
	s_mov_b32 s39, 0x40000
	s_mov_b32 s40, 0x60000
	s_movk_i32 s41, 0x1600
	s_movk_i32 s42, 0x5800
	s_movk_i32 s43, 0xe08
	s_movk_i32 s44, 0x3820
	v_readlane_b32 s45, v252, 48
	s_branch .LBB0_4
